# P2 epilogue silu/sigmoid tiles: scale, +1 and final product as packed f32 ops (same results, fewer VALU issues)
# baseline (speedup 1.0000x reference)
; __device__ __forceinline__ void st_bf4(bf16_t* p, f32x4 v) { u32x2 w; w.x = pk2(v[0], v[1]); w.y = pk2(v[2], v[3]); *(u32x2*)p = w; }
; __device__ __forceinline__ float sigmoidf_(float x) { return __builtin_amdgcn_rcpf(1.f + __expf(-x)); }
;     __device__ __forceinline__ void put(const Unit& u, int row, int col, f32x4 v) const {
;     ...
;         if (act == 1) v = v * 0.08838834764831845f;
;         else if (act == 2) { v[0] *= sigmoidf_(v[0]); v[1] *= sigmoidf_(v[1]); v[2] *= sigmoidf_(v[2]); v[3] *= sigmoidf_(v[3]); }
;         else if (act == 3) { v[0] = sigmoidf_(v[0]); v[1] = sigmoidf_(v[1]); v[2] = sigmoidf_(v[2]); v[3] = sigmoidf_(v[3]); }
;         st_bf4(base + (size_t)row * ldc + (col - c0), v);
.Lp2e_v_silu:
	s_mov_b32 s98, 0xbfb8aa3b
	s_mov_b32 s99, 0xbfb8aa3b
	s_mov_b32 s100, 1.0
	s_mov_b32 s101, 1.0
	v_pk_mul_f32 v[152:153], v[124:125], s[98:99]
	v_pk_mul_f32 v[154:155], v[126:127], s[98:99]
	v_pk_mul_f32 v[156:157], v[120:121], s[98:99]
	v_pk_mul_f32 v[158:159], v[122:123], s[98:99]
	v_exp_f32_e32 v152, v152
	v_exp_f32_e32 v153, v153
	v_exp_f32_e32 v154, v154
	v_exp_f32_e32 v155, v155
	v_exp_f32_e32 v156, v156
	v_exp_f32_e32 v157, v157
	v_exp_f32_e32 v158, v158
	v_exp_f32_e32 v159, v159
	v_pk_add_f32 v[152:153], v[152:153], s[100:101]
	v_pk_add_f32 v[154:155], v[154:155], s[100:101]
	v_pk_add_f32 v[156:157], v[156:157], s[100:101]
	v_pk_add_f32 v[158:159], v[158:159], s[100:101]
	v_rcp_f32_e32 v152, v152
	v_rcp_f32_e32 v153, v153
	v_rcp_f32_e32 v154, v154
	v_rcp_f32_e32 v155, v155
	v_rcp_f32_e32 v156, v156
	v_rcp_f32_e32 v157, v157
	v_rcp_f32_e32 v158, v158
	v_rcp_f32_e32 v159, v159
	v_pk_mul_f32 v[124:125], v[124:125], v[152:153]
	v_pk_mul_f32 v[126:127], v[126:127], v[154:155]
	v_pk_mul_f32 v[120:121], v[120:121], v[156:157]
	v_pk_mul_f32 v[122:123], v[122:123], v[158:159]
	v_cvt_pk_bf16_f32 v124, v124, v125
	v_cvt_pk_bf16_f32 v125, v126, v127
	v_cvt_pk_bf16_f32 v126, v120, v121
	v_cvt_pk_bf16_f32 v127, v122, v123
	s_nop 1
	v_permlane16_swap_b32_e32 v124, v126
	v_permlane16_swap_b32_e32 v125, v127
	global_store_dwordx4 v[150:151], v[124:127], off
	v_pk_mul_f32 v[152:153], v[116:117], s[98:99]
	v_pk_mul_f32 v[154:155], v[118:119], s[98:99]
	v_pk_mul_f32 v[156:157], v[112:113], s[98:99]
	v_pk_mul_f32 v[158:159], v[114:115], s[98:99]
	v_exp_f32_e32 v152, v152
	v_exp_f32_e32 v153, v153
	v_exp_f32_e32 v154, v154
	v_exp_f32_e32 v155, v155
	v_exp_f32_e32 v156, v156
	v_exp_f32_e32 v157, v157
	v_exp_f32_e32 v158, v158
	v_exp_f32_e32 v159, v159
	v_pk_add_f32 v[152:153], v[152:153], s[100:101]
	v_pk_add_f32 v[154:155], v[154:155], s[100:101]
	v_pk_add_f32 v[156:157], v[156:157], s[100:101]
	v_pk_add_f32 v[158:159], v[158:159], s[100:101]
	v_rcp_f32_e32 v152, v152
	v_rcp_f32_e32 v153, v153
	v_rcp_f32_e32 v154, v154
	v_rcp_f32_e32 v155, v155
	v_rcp_f32_e32 v156, v156
	v_rcp_f32_e32 v157, v157
	v_rcp_f32_e32 v158, v158
	v_rcp_f32_e32 v159, v159
	v_pk_mul_f32 v[116:117], v[116:117], v[152:153]
	v_pk_mul_f32 v[118:119], v[118:119], v[154:155]
	v_pk_mul_f32 v[112:113], v[112:113], v[156:157]
	v_pk_mul_f32 v[114:115], v[114:115], v[158:159]
	v_cvt_pk_bf16_f32 v116, v116, v117
	v_cvt_pk_bf16_f32 v117, v118, v119
	v_cvt_pk_bf16_f32 v118, v112, v113
	v_cvt_pk_bf16_f32 v119, v114, v115
	s_nop 1
	v_permlane16_swap_b32_e32 v116, v118
	v_permlane16_swap_b32_e32 v117, v119
	global_store_dwordx4 v[150:151], v[116:119], off offset:256
	s_nop 0
	v_lshl_add_u64 v[150:151], v[150:151], 0, s[44:45]
	v_pk_mul_f32 v[152:153], v[108:109], s[98:99]
	v_pk_mul_f32 v[154:155], v[110:111], s[98:99]
	v_pk_mul_f32 v[156:157], v[104:105], s[98:99]
	v_pk_mul_f32 v[158:159], v[106:107], s[98:99]
	v_exp_f32_e32 v152, v152
	v_exp_f32_e32 v153, v153
	v_exp_f32_e32 v154, v154
	v_exp_f32_e32 v155, v155
	v_exp_f32_e32 v156, v156
	v_exp_f32_e32 v157, v157
	v_exp_f32_e32 v158, v158
	v_exp_f32_e32 v159, v159
	v_pk_add_f32 v[152:153], v[152:153], s[100:101]
	v_pk_add_f32 v[154:155], v[154:155], s[100:101]
	v_pk_add_f32 v[156:157], v[156:157], s[100:101]
	v_pk_add_f32 v[158:159], v[158:159], s[100:101]
	v_rcp_f32_e32 v152, v152
	v_rcp_f32_e32 v153, v153
	v_rcp_f32_e32 v154, v154
	v_rcp_f32_e32 v155, v155
	v_rcp_f32_e32 v156, v156
	v_rcp_f32_e32 v157, v157
	v_rcp_f32_e32 v158, v158
	v_rcp_f32_e32 v159, v159
	v_pk_mul_f32 v[108:109], v[108:109], v[152:153]
	v_pk_mul_f32 v[110:111], v[110:111], v[154:155]
	v_pk_mul_f32 v[104:105], v[104:105], v[156:157]
	v_pk_mul_f32 v[106:107], v[106:107], v[158:159]
	v_cvt_pk_bf16_f32 v108, v108, v109
	v_cvt_pk_bf16_f32 v109, v110, v111
	v_cvt_pk_bf16_f32 v110, v104, v105
	v_cvt_pk_bf16_f32 v111, v106, v107
	s_nop 1
	v_permlane16_swap_b32_e32 v108, v110
	v_permlane16_swap_b32_e32 v109, v111
	global_store_dwordx4 v[150:151], v[108:111], off
	v_pk_mul_f32 v[152:153], v[100:101], s[98:99]
	v_pk_mul_f32 v[154:155], v[102:103], s[98:99]
	v_pk_mul_f32 v[156:157], v[96:97], s[98:99]
	v_pk_mul_f32 v[158:159], v[98:99], s[98:99]
	v_exp_f32_e32 v152, v152
	v_exp_f32_e32 v153, v153
	v_exp_f32_e32 v154, v154
	v_exp_f32_e32 v155, v155
	v_exp_f32_e32 v156, v156
	v_exp_f32_e32 v157, v157
	v_exp_f32_e32 v158, v158
	v_exp_f32_e32 v159, v159
	v_pk_add_f32 v[152:153], v[152:153], s[100:101]
	v_pk_add_f32 v[154:155], v[154:155], s[100:101]
	v_pk_add_f32 v[156:157], v[156:157], s[100:101]
	v_pk_add_f32 v[158:159], v[158:159], s[100:101]
	v_rcp_f32_e32 v152, v152
	v_rcp_f32_e32 v153, v153
	v_rcp_f32_e32 v154, v154
	v_rcp_f32_e32 v155, v155
	v_rcp_f32_e32 v156, v156
	v_rcp_f32_e32 v157, v157
	v_rcp_f32_e32 v158, v158
	v_rcp_f32_e32 v159, v159
	v_pk_mul_f32 v[100:101], v[100:101], v[152:153]
	v_pk_mul_f32 v[102:103], v[102:103], v[154:155]
	v_pk_mul_f32 v[96:97], v[96:97], v[156:157]
	v_pk_mul_f32 v[98:99], v[98:99], v[158:159]
	v_cvt_pk_bf16_f32 v100, v100, v101
	v_cvt_pk_bf16_f32 v101, v102, v103
	v_cvt_pk_bf16_f32 v102, v96, v97
	v_cvt_pk_bf16_f32 v103, v98, v99
	s_nop 1
	v_permlane16_swap_b32_e32 v100, v102
	v_permlane16_swap_b32_e32 v101, v103
	global_store_dwordx4 v[150:151], v[100:103], off offset:256
	s_nop 0
	v_lshl_add_u64 v[150:151], v[150:151], 0, s[44:45]
	v_pk_mul_f32 v[152:153], v[92:93], s[98:99]
	v_pk_mul_f32 v[154:155], v[94:95], s[98:99]
	v_pk_mul_f32 v[156:157], v[88:89], s[98:99]
	v_pk_mul_f32 v[158:159], v[90:91], s[98:99]
	v_exp_f32_e32 v152, v152
	v_exp_f32_e32 v153, v153
	v_exp_f32_e32 v154, v154
	v_exp_f32_e32 v155, v155
	v_exp_f32_e32 v156, v156
; __device__ __forceinline__ void st_bf4(bf16_t* p, f32x4 v) { u32x2 w; w.x = pk2(v[0], v[1]); w.y = pk2(v[2], v[3]); *(u32x2*)p = w; }
; __device__ __forceinline__ float sigmoidf_(float x) { return __builtin_amdgcn_rcpf(1.f + __expf(-x)); }
;     __device__ __forceinline__ void put(const Unit& u, int row, int col, f32x4 v) const {
;     ...
;         if (act == 1) v = v * 0.08838834764831845f;
;         else if (act == 2) { v[0] *= sigmoidf_(v[0]); v[1] *= sigmoidf_(v[1]); v[2] *= sigmoidf_(v[2]); v[3] *= sigmoidf_(v[3]); }
;         else if (act == 3) { v[0] = sigmoidf_(v[0]); v[1] = sigmoidf_(v[1]); v[2] = sigmoidf_(v[2]); v[3] = sigmoidf_(v[3]); }
;         st_bf4(base + (size_t)row * ldc + (col - c0), v);
	v_exp_f32_e32 v157, v157
	v_exp_f32_e32 v158, v158
	v_exp_f32_e32 v159, v159
	v_pk_add_f32 v[152:153], v[152:153], s[100:101]
	v_pk_add_f32 v[154:155], v[154:155], s[100:101]
	v_pk_add_f32 v[156:157], v[156:157], s[100:101]
	v_pk_add_f32 v[158:159], v[158:159], s[100:101]
	v_rcp_f32_e32 v152, v152
	v_rcp_f32_e32 v153, v153
	v_rcp_f32_e32 v154, v154
	v_rcp_f32_e32 v155, v155
	v_rcp_f32_e32 v156, v156
	v_rcp_f32_e32 v157, v157
	v_rcp_f32_e32 v158, v158
	v_rcp_f32_e32 v159, v159
	v_pk_mul_f32 v[92:93], v[92:93], v[152:153]
	v_pk_mul_f32 v[94:95], v[94:95], v[154:155]
	v_pk_mul_f32 v[88:89], v[88:89], v[156:157]
	v_pk_mul_f32 v[90:91], v[90:91], v[158:159]
	v_cvt_pk_bf16_f32 v92, v92, v93
	v_cvt_pk_bf16_f32 v93, v94, v95
	v_cvt_pk_bf16_f32 v94, v88, v89
	v_cvt_pk_bf16_f32 v95, v90, v91
	s_nop 1
	v_permlane16_swap_b32_e32 v92, v94
	v_permlane16_swap_b32_e32 v93, v95
	global_store_dwordx4 v[150:151], v[92:95], off
	v_pk_mul_f32 v[152:153], v[84:85], s[98:99]
	v_pk_mul_f32 v[154:155], v[86:87], s[98:99]
	v_pk_mul_f32 v[156:157], v[80:81], s[98:99]
	v_pk_mul_f32 v[158:159], v[82:83], s[98:99]
	v_exp_f32_e32 v152, v152
	v_exp_f32_e32 v153, v153
	v_exp_f32_e32 v154, v154
	v_exp_f32_e32 v155, v155
	v_exp_f32_e32 v156, v156
	v_exp_f32_e32 v157, v157
	v_exp_f32_e32 v158, v158
	v_exp_f32_e32 v159, v159
	v_pk_add_f32 v[152:153], v[152:153], s[100:101]
	v_pk_add_f32 v[154:155], v[154:155], s[100:101]
	v_pk_add_f32 v[156:157], v[156:157], s[100:101]
	v_pk_add_f32 v[158:159], v[158:159], s[100:101]
	v_rcp_f32_e32 v152, v152
	v_rcp_f32_e32 v153, v153
	v_rcp_f32_e32 v154, v154
	v_rcp_f32_e32 v155, v155
	v_rcp_f32_e32 v156, v156
	v_rcp_f32_e32 v157, v157
	v_rcp_f32_e32 v158, v158
	v_rcp_f32_e32 v159, v159
	v_pk_mul_f32 v[84:85], v[84:85], v[152:153]
	v_pk_mul_f32 v[86:87], v[86:87], v[154:155]
	v_pk_mul_f32 v[80:81], v[80:81], v[156:157]
	v_pk_mul_f32 v[82:83], v[82:83], v[158:159]
	v_cvt_pk_bf16_f32 v84, v84, v85
	v_cvt_pk_bf16_f32 v85, v86, v87
	v_cvt_pk_bf16_f32 v86, v80, v81
	v_cvt_pk_bf16_f32 v87, v82, v83
	s_nop 1
	v_permlane16_swap_b32_e32 v84, v86
	v_permlane16_swap_b32_e32 v85, v87
	global_store_dwordx4 v[150:151], v[84:87], off offset:256
	s_nop 0
	v_lshl_add_u64 v[150:151], v[150:151], 0, s[44:45]
	v_pk_mul_f32 v[152:153], v[76:77], s[98:99]
	v_pk_mul_f32 v[154:155], v[78:79], s[98:99]
	v_pk_mul_f32 v[156:157], v[72:73], s[98:99]
	v_pk_mul_f32 v[158:159], v[74:75], s[98:99]
	v_exp_f32_e32 v152, v152
	v_exp_f32_e32 v153, v153
	v_exp_f32_e32 v154, v154
	v_exp_f32_e32 v155, v155
	v_exp_f32_e32 v156, v156
	v_exp_f32_e32 v157, v157
	v_exp_f32_e32 v158, v158
	v_exp_f32_e32 v159, v159
	v_pk_add_f32 v[152:153], v[152:153], s[100:101]
	v_pk_add_f32 v[154:155], v[154:155], s[100:101]
	v_pk_add_f32 v[156:157], v[156:157], s[100:101]
	v_pk_add_f32 v[158:159], v[158:159], s[100:101]
	v_rcp_f32_e32 v152, v152
	v_rcp_f32_e32 v153, v153
	v_rcp_f32_e32 v154, v154
	v_rcp_f32_e32 v155, v155
	v_rcp_f32_e32 v156, v156
	v_rcp_f32_e32 v157, v157
	v_rcp_f32_e32 v158, v158
	v_rcp_f32_e32 v159, v159
	v_pk_mul_f32 v[76:77], v[76:77], v[152:153]
	v_pk_mul_f32 v[78:79], v[78:79], v[154:155]
	v_pk_mul_f32 v[72:73], v[72:73], v[156:157]
	v_pk_mul_f32 v[74:75], v[74:75], v[158:159]
	v_cvt_pk_bf16_f32 v76, v76, v77
	v_cvt_pk_bf16_f32 v77, v78, v79
	v_cvt_pk_bf16_f32 v78, v72, v73
	v_cvt_pk_bf16_f32 v79, v74, v75
	s_nop 1
	v_permlane16_swap_b32_e32 v76, v78
	v_permlane16_swap_b32_e32 v77, v79
	global_store_dwordx4 v[150:151], v[76:79], off
	v_pk_mul_f32 v[152:153], v[68:69], s[98:99]
	v_pk_mul_f32 v[154:155], v[70:71], s[98:99]
	v_pk_mul_f32 v[156:157], v[64:65], s[98:99]
	v_pk_mul_f32 v[158:159], v[66:67], s[98:99]
	v_exp_f32_e32 v152, v152
	v_exp_f32_e32 v153, v153
	v_exp_f32_e32 v154, v154
	v_exp_f32_e32 v155, v155
	v_exp_f32_e32 v156, v156
	v_exp_f32_e32 v157, v157
	v_exp_f32_e32 v158, v158
	v_exp_f32_e32 v159, v159
	v_pk_add_f32 v[152:153], v[152:153], s[100:101]
	v_pk_add_f32 v[154:155], v[154:155], s[100:101]
	v_pk_add_f32 v[156:157], v[156:157], s[100:101]
	v_pk_add_f32 v[158:159], v[158:159], s[100:101]
	v_rcp_f32_e32 v152, v152
	v_rcp_f32_e32 v153, v153
	v_rcp_f32_e32 v154, v154
	v_rcp_f32_e32 v155, v155
	v_rcp_f32_e32 v156, v156
	v_rcp_f32_e32 v157, v157
	v_rcp_f32_e32 v158, v158
	v_rcp_f32_e32 v159, v159
	v_pk_mul_f32 v[68:69], v[68:69], v[152:153]
	v_pk_mul_f32 v[70:71], v[70:71], v[154:155]
	v_pk_mul_f32 v[64:65], v[64:65], v[156:157]
	v_pk_mul_f32 v[66:67], v[66:67], v[158:159]
	v_cvt_pk_bf16_f32 v68, v68, v69
	v_cvt_pk_bf16_f32 v69, v70, v71
	v_cvt_pk_bf16_f32 v70, v64, v65
	v_cvt_pk_bf16_f32 v71, v66, v67
	s_nop 1
	v_permlane16_swap_b32_e32 v68, v70
	v_permlane16_swap_b32_e32 v69, v71
	global_store_dwordx4 v[150:151], v[68:71], off offset:256
	s_nop 0
	v_lshl_add_u64 v[150:151], v[150:151], 0, s[44:45]
	v_lshl_add_u64 v[150:151], v[150:151], 0, s[46:47]
	v_pk_mul_f32 v[152:153], v[60:61], s[98:99]
	v_pk_mul_f32 v[154:155], v[62:63], s[98:99]
	v_pk_mul_f32 v[156:157], v[56:57], s[98:99]
	v_pk_mul_f32 v[158:159], v[58:59], s[98:99]
	v_exp_f32_e32 v152, v152
	v_exp_f32_e32 v153, v153
	v_exp_f32_e32 v154, v154
	v_exp_f32_e32 v155, v155
	v_exp_f32_e32 v156, v156
	v_exp_f32_e32 v157, v157
	v_exp_f32_e32 v158, v158
	v_exp_f32_e32 v159, v159
	v_pk_add_f32 v[152:153], v[152:153], s[100:101]
	v_pk_add_f32 v[154:155], v[154:155], s[100:101]
	v_pk_add_f32 v[156:157], v[156:157], s[100:101]
	v_pk_add_f32 v[158:159], v[158:159], s[100:101]
	v_rcp_f32_e32 v152, v152
	v_rcp_f32_e32 v153, v153
	v_rcp_f32_e32 v154, v154
	v_rcp_f32_e32 v155, v155
	v_rcp_f32_e32 v156, v156
	v_rcp_f32_e32 v157, v157
	v_rcp_f32_e32 v158, v158
	v_rcp_f32_e32 v159, v159
	v_pk_mul_f32 v[60:61], v[60:61], v[152:153]
; __device__ __forceinline__ void st_bf4(bf16_t* p, f32x4 v) { u32x2 w; w.x = pk2(v[0], v[1]); w.y = pk2(v[2], v[3]); *(u32x2*)p = w; }
; __device__ __forceinline__ float sigmoidf_(float x) { return __builtin_amdgcn_rcpf(1.f + __expf(-x)); }
;     __device__ __forceinline__ void put(const Unit& u, int row, int col, f32x4 v) const {
;     ...
;         if (act == 1) v = v * 0.08838834764831845f;
;         else if (act == 2) { v[0] *= sigmoidf_(v[0]); v[1] *= sigmoidf_(v[1]); v[2] *= sigmoidf_(v[2]); v[3] *= sigmoidf_(v[3]); }
;         else if (act == 3) { v[0] = sigmoidf_(v[0]); v[1] = sigmoidf_(v[1]); v[2] = sigmoidf_(v[2]); v[3] = sigmoidf_(v[3]); }
;         st_bf4(base + (size_t)row * ldc + (col - c0), v);
	v_pk_mul_f32 v[62:63], v[62:63], v[154:155]
	v_pk_mul_f32 v[56:57], v[56:57], v[156:157]
	v_pk_mul_f32 v[58:59], v[58:59], v[158:159]
	v_cvt_pk_bf16_f32 v60, v60, v61
	v_cvt_pk_bf16_f32 v61, v62, v63
	v_cvt_pk_bf16_f32 v62, v56, v57
	v_cvt_pk_bf16_f32 v63, v58, v59
	s_nop 1
	v_permlane16_swap_b32_e32 v60, v62
	v_permlane16_swap_b32_e32 v61, v63
	global_store_dwordx4 v[150:151], v[60:63], off
	v_pk_mul_f32 v[152:153], v[52:53], s[98:99]
	v_pk_mul_f32 v[154:155], v[54:55], s[98:99]
	v_pk_mul_f32 v[156:157], v[48:49], s[98:99]
	v_pk_mul_f32 v[158:159], v[50:51], s[98:99]
	v_exp_f32_e32 v152, v152
	v_exp_f32_e32 v153, v153
	v_exp_f32_e32 v154, v154
	v_exp_f32_e32 v155, v155
	v_exp_f32_e32 v156, v156
	v_exp_f32_e32 v157, v157
	v_exp_f32_e32 v158, v158
	v_exp_f32_e32 v159, v159
	v_pk_add_f32 v[152:153], v[152:153], s[100:101]
	v_pk_add_f32 v[154:155], v[154:155], s[100:101]
	v_pk_add_f32 v[156:157], v[156:157], s[100:101]
	v_pk_add_f32 v[158:159], v[158:159], s[100:101]
	v_rcp_f32_e32 v152, v152
	v_rcp_f32_e32 v153, v153
	v_rcp_f32_e32 v154, v154
	v_rcp_f32_e32 v155, v155
	v_rcp_f32_e32 v156, v156
	v_rcp_f32_e32 v157, v157
	v_rcp_f32_e32 v158, v158
	v_rcp_f32_e32 v159, v159
	v_pk_mul_f32 v[52:53], v[52:53], v[152:153]
	v_pk_mul_f32 v[54:55], v[54:55], v[154:155]
	v_pk_mul_f32 v[48:49], v[48:49], v[156:157]
	v_pk_mul_f32 v[50:51], v[50:51], v[158:159]
	v_cvt_pk_bf16_f32 v52, v52, v53
	v_cvt_pk_bf16_f32 v53, v54, v55
	v_cvt_pk_bf16_f32 v54, v48, v49
	v_cvt_pk_bf16_f32 v55, v50, v51
	s_nop 1
	v_permlane16_swap_b32_e32 v52, v54
	v_permlane16_swap_b32_e32 v53, v55
	global_store_dwordx4 v[150:151], v[52:55], off offset:256
	s_nop 0
	v_lshl_add_u64 v[150:151], v[150:151], 0, s[44:45]
	v_pk_mul_f32 v[152:153], v[44:45], s[98:99]
	v_pk_mul_f32 v[154:155], v[46:47], s[98:99]
	v_pk_mul_f32 v[156:157], v[40:41], s[98:99]
	v_pk_mul_f32 v[158:159], v[42:43], s[98:99]
	v_exp_f32_e32 v152, v152
	v_exp_f32_e32 v153, v153
	v_exp_f32_e32 v154, v154
	v_exp_f32_e32 v155, v155
	v_exp_f32_e32 v156, v156
	v_exp_f32_e32 v157, v157
	v_exp_f32_e32 v158, v158
	v_exp_f32_e32 v159, v159
	v_pk_add_f32 v[152:153], v[152:153], s[100:101]
	v_pk_add_f32 v[154:155], v[154:155], s[100:101]
	v_pk_add_f32 v[156:157], v[156:157], s[100:101]
	v_pk_add_f32 v[158:159], v[158:159], s[100:101]
	v_rcp_f32_e32 v152, v152
	v_rcp_f32_e32 v153, v153
	v_rcp_f32_e32 v154, v154
	v_rcp_f32_e32 v155, v155
	v_rcp_f32_e32 v156, v156
	v_rcp_f32_e32 v157, v157
	v_rcp_f32_e32 v158, v158
	v_rcp_f32_e32 v159, v159
	v_pk_mul_f32 v[44:45], v[44:45], v[152:153]
	v_pk_mul_f32 v[46:47], v[46:47], v[154:155]
	v_pk_mul_f32 v[40:41], v[40:41], v[156:157]
	v_pk_mul_f32 v[42:43], v[42:43], v[158:159]
	v_cvt_pk_bf16_f32 v44, v44, v45
	v_cvt_pk_bf16_f32 v45, v46, v47
	v_cvt_pk_bf16_f32 v46, v40, v41
	v_cvt_pk_bf16_f32 v47, v42, v43
	s_nop 1
	v_permlane16_swap_b32_e32 v44, v46
	v_permlane16_swap_b32_e32 v45, v47
	global_store_dwordx4 v[150:151], v[44:47], off
	v_pk_mul_f32 v[152:153], v[36:37], s[98:99]
	v_pk_mul_f32 v[154:155], v[38:39], s[98:99]
	v_pk_mul_f32 v[156:157], v[32:33], s[98:99]
	v_pk_mul_f32 v[158:159], v[34:35], s[98:99]
	v_exp_f32_e32 v152, v152
	v_exp_f32_e32 v153, v153
	v_exp_f32_e32 v154, v154
	v_exp_f32_e32 v155, v155
	v_exp_f32_e32 v156, v156
	v_exp_f32_e32 v157, v157
	v_exp_f32_e32 v158, v158
	v_exp_f32_e32 v159, v159
	v_pk_add_f32 v[152:153], v[152:153], s[100:101]
	v_pk_add_f32 v[154:155], v[154:155], s[100:101]
	v_pk_add_f32 v[156:157], v[156:157], s[100:101]
	v_pk_add_f32 v[158:159], v[158:159], s[100:101]
	v_rcp_f32_e32 v152, v152
	v_rcp_f32_e32 v153, v153
	v_rcp_f32_e32 v154, v154
	v_rcp_f32_e32 v155, v155
	v_rcp_f32_e32 v156, v156
	v_rcp_f32_e32 v157, v157
	v_rcp_f32_e32 v158, v158
	v_rcp_f32_e32 v159, v159
	v_pk_mul_f32 v[36:37], v[36:37], v[152:153]
	v_pk_mul_f32 v[38:39], v[38:39], v[154:155]
	v_pk_mul_f32 v[32:33], v[32:33], v[156:157]
	v_pk_mul_f32 v[34:35], v[34:35], v[158:159]
	v_cvt_pk_bf16_f32 v36, v36, v37
	v_cvt_pk_bf16_f32 v37, v38, v39
	v_cvt_pk_bf16_f32 v38, v32, v33
	v_cvt_pk_bf16_f32 v39, v34, v35
	s_nop 1
	v_permlane16_swap_b32_e32 v36, v38
	v_permlane16_swap_b32_e32 v37, v39
	global_store_dwordx4 v[150:151], v[36:39], off offset:256
	s_nop 0
	v_lshl_add_u64 v[150:151], v[150:151], 0, s[44:45]
	v_pk_mul_f32 v[152:153], v[28:29], s[98:99]
	v_pk_mul_f32 v[154:155], v[30:31], s[98:99]
	v_pk_mul_f32 v[156:157], v[24:25], s[98:99]
	v_pk_mul_f32 v[158:159], v[26:27], s[98:99]
	v_exp_f32_e32 v152, v152
	v_exp_f32_e32 v153, v153
	v_exp_f32_e32 v154, v154
	v_exp_f32_e32 v155, v155
	v_exp_f32_e32 v156, v156
	v_exp_f32_e32 v157, v157
	v_exp_f32_e32 v158, v158
	v_exp_f32_e32 v159, v159
	v_pk_add_f32 v[152:153], v[152:153], s[100:101]
	v_pk_add_f32 v[154:155], v[154:155], s[100:101]
	v_pk_add_f32 v[156:157], v[156:157], s[100:101]
	v_pk_add_f32 v[158:159], v[158:159], s[100:101]
	v_rcp_f32_e32 v152, v152
	v_rcp_f32_e32 v153, v153
	v_rcp_f32_e32 v154, v154
	v_rcp_f32_e32 v155, v155
	v_rcp_f32_e32 v156, v156
	v_rcp_f32_e32 v157, v157
	v_rcp_f32_e32 v158, v158
	v_rcp_f32_e32 v159, v159
	v_pk_mul_f32 v[28:29], v[28:29], v[152:153]
	v_pk_mul_f32 v[30:31], v[30:31], v[154:155]
	v_pk_mul_f32 v[24:25], v[24:25], v[156:157]
	v_pk_mul_f32 v[26:27], v[26:27], v[158:159]
	v_cvt_pk_bf16_f32 v28, v28, v29
	v_cvt_pk_bf16_f32 v29, v30, v31
	v_cvt_pk_bf16_f32 v30, v24, v25
	v_cvt_pk_bf16_f32 v31, v26, v27
	s_nop 1
	v_permlane16_swap_b32_e32 v28, v30
	v_permlane16_swap_b32_e32 v29, v31
	global_store_dwordx4 v[150:151], v[28:31], off
	v_pk_mul_f32 v[152:153], v[20:21], s[98:99]
	v_pk_mul_f32 v[154:155], v[22:23], s[98:99]
	v_pk_mul_f32 v[156:157], v[16:17], s[98:99]
	v_pk_mul_f32 v[158:159], v[18:19], s[98:99]
; __device__ __forceinline__ void st_bf4(bf16_t* p, f32x4 v) { u32x2 w; w.x = pk2(v[0], v[1]); w.y = pk2(v[2], v[3]); *(u32x2*)p = w; }
; __device__ __forceinline__ float sigmoidf_(float x) { return __builtin_amdgcn_rcpf(1.f + __expf(-x)); }
;     __device__ __forceinline__ void put(const Unit& u, int row, int col, f32x4 v) const {
;     ...
;         if (act == 1) v = v * 0.08838834764831845f;
;         else if (act == 2) { v[0] *= sigmoidf_(v[0]); v[1] *= sigmoidf_(v[1]); v[2] *= sigmoidf_(v[2]); v[3] *= sigmoidf_(v[3]); }
;         else if (act == 3) { v[0] = sigmoidf_(v[0]); v[1] = sigmoidf_(v[1]); v[2] = sigmoidf_(v[2]); v[3] = sigmoidf_(v[3]); }
;         st_bf4(base + (size_t)row * ldc + (col - c0), v);
	v_exp_f32_e32 v152, v152
	v_exp_f32_e32 v153, v153
	v_exp_f32_e32 v154, v154
	v_exp_f32_e32 v155, v155
	v_exp_f32_e32 v156, v156
	v_exp_f32_e32 v157, v157
	v_exp_f32_e32 v158, v158
	v_exp_f32_e32 v159, v159
	v_pk_add_f32 v[152:153], v[152:153], s[100:101]
	v_pk_add_f32 v[154:155], v[154:155], s[100:101]
	v_pk_add_f32 v[156:157], v[156:157], s[100:101]
	v_pk_add_f32 v[158:159], v[158:159], s[100:101]
	v_rcp_f32_e32 v152, v152
	v_rcp_f32_e32 v153, v153
	v_rcp_f32_e32 v154, v154
	v_rcp_f32_e32 v155, v155
	v_rcp_f32_e32 v156, v156
	v_rcp_f32_e32 v157, v157
	v_rcp_f32_e32 v158, v158
	v_rcp_f32_e32 v159, v159
	v_pk_mul_f32 v[20:21], v[20:21], v[152:153]
	v_pk_mul_f32 v[22:23], v[22:23], v[154:155]
	v_pk_mul_f32 v[16:17], v[16:17], v[156:157]
	v_pk_mul_f32 v[18:19], v[18:19], v[158:159]
	v_cvt_pk_bf16_f32 v20, v20, v21
	v_cvt_pk_bf16_f32 v21, v22, v23
	v_cvt_pk_bf16_f32 v22, v16, v17
	v_cvt_pk_bf16_f32 v23, v18, v19
	s_nop 1
	v_permlane16_swap_b32_e32 v20, v22
	v_permlane16_swap_b32_e32 v21, v23
	global_store_dwordx4 v[150:151], v[20:23], off offset:256
	s_nop 0
	v_lshl_add_u64 v[150:151], v[150:151], 0, s[44:45]
	v_pk_mul_f32 v[152:153], v[12:13], s[98:99]
	v_pk_mul_f32 v[154:155], v[14:15], s[98:99]
	v_pk_mul_f32 v[156:157], v[8:9], s[98:99]
	v_pk_mul_f32 v[158:159], v[10:11], s[98:99]
	v_exp_f32_e32 v152, v152
	v_exp_f32_e32 v153, v153
	v_exp_f32_e32 v154, v154
	v_exp_f32_e32 v155, v155
	v_exp_f32_e32 v156, v156
	v_exp_f32_e32 v157, v157
	v_exp_f32_e32 v158, v158
	v_exp_f32_e32 v159, v159
	v_pk_add_f32 v[152:153], v[152:153], s[100:101]
	v_pk_add_f32 v[154:155], v[154:155], s[100:101]
	v_pk_add_f32 v[156:157], v[156:157], s[100:101]
	v_pk_add_f32 v[158:159], v[158:159], s[100:101]
	v_rcp_f32_e32 v152, v152
	v_rcp_f32_e32 v153, v153
	v_rcp_f32_e32 v154, v154
	v_rcp_f32_e32 v155, v155
	v_rcp_f32_e32 v156, v156
	v_rcp_f32_e32 v157, v157
	v_rcp_f32_e32 v158, v158
	v_rcp_f32_e32 v159, v159
	v_pk_mul_f32 v[12:13], v[12:13], v[152:153]
	v_pk_mul_f32 v[14:15], v[14:15], v[154:155]
	v_pk_mul_f32 v[8:9], v[8:9], v[156:157]
	v_pk_mul_f32 v[10:11], v[10:11], v[158:159]
	v_cvt_pk_bf16_f32 v12, v12, v13
	v_cvt_pk_bf16_f32 v13, v14, v15
	v_cvt_pk_bf16_f32 v14, v8, v9
	v_cvt_pk_bf16_f32 v15, v10, v11
	s_nop 1
	v_permlane16_swap_b32_e32 v12, v14
	v_permlane16_swap_b32_e32 v13, v15
	global_store_dwordx4 v[150:151], v[12:15], off
	v_pk_mul_f32 v[152:153], v[4:5], s[98:99]
	v_pk_mul_f32 v[154:155], v[6:7], s[98:99]
	v_pk_mul_f32 v[156:157], v[0:1], s[98:99]
	v_pk_mul_f32 v[158:159], v[2:3], s[98:99]
	v_exp_f32_e32 v152, v152
	v_exp_f32_e32 v153, v153
	v_exp_f32_e32 v154, v154
	v_exp_f32_e32 v155, v155
	v_exp_f32_e32 v156, v156
	v_exp_f32_e32 v157, v157
	v_exp_f32_e32 v158, v158
	v_exp_f32_e32 v159, v159
	v_pk_add_f32 v[152:153], v[152:153], s[100:101]
	v_pk_add_f32 v[154:155], v[154:155], s[100:101]
	v_pk_add_f32 v[156:157], v[156:157], s[100:101]
	v_pk_add_f32 v[158:159], v[158:159], s[100:101]
	v_rcp_f32_e32 v152, v152
	v_rcp_f32_e32 v153, v153
	v_rcp_f32_e32 v154, v154
	v_rcp_f32_e32 v155, v155
	v_rcp_f32_e32 v156, v156
	v_rcp_f32_e32 v157, v157
	v_rcp_f32_e32 v158, v158
	v_rcp_f32_e32 v159, v159
	v_pk_mul_f32 v[4:5], v[4:5], v[152:153]
	v_pk_mul_f32 v[6:7], v[6:7], v[154:155]
	v_pk_mul_f32 v[0:1], v[0:1], v[156:157]
	v_pk_mul_f32 v[2:3], v[2:3], v[158:159]
	v_cvt_pk_bf16_f32 v4, v4, v5
	v_cvt_pk_bf16_f32 v5, v6, v7
	v_cvt_pk_bf16_f32 v6, v0, v1
	v_cvt_pk_bf16_f32 v7, v2, v3
	s_nop 1
	v_permlane16_swap_b32_e32 v4, v6
	v_permlane16_swap_b32_e32 v5, v7
	global_store_dwordx4 v[150:151], v[4:7], off offset:256
	s_branch .Lp2e_done
.Lp2e_v_sigm:
	s_mov_b32 s98, 0xbfb8aa3b
	s_mov_b32 s99, 0xbfb8aa3b
	s_mov_b32 s100, 1.0
	s_mov_b32 s101, 1.0
	v_pk_mul_f32 v[152:153], v[124:125], s[98:99]
	v_pk_mul_f32 v[154:155], v[126:127], s[98:99]
	v_pk_mul_f32 v[156:157], v[120:121], s[98:99]
	v_pk_mul_f32 v[158:159], v[122:123], s[98:99]
	v_exp_f32_e32 v152, v152
	v_exp_f32_e32 v153, v153
	v_exp_f32_e32 v154, v154
	v_exp_f32_e32 v155, v155
	v_exp_f32_e32 v156, v156
	v_exp_f32_e32 v157, v157
	v_exp_f32_e32 v158, v158
	v_exp_f32_e32 v159, v159
	v_pk_add_f32 v[152:153], v[152:153], s[100:101]
	v_pk_add_f32 v[154:155], v[154:155], s[100:101]
	v_pk_add_f32 v[156:157], v[156:157], s[100:101]
	v_pk_add_f32 v[158:159], v[158:159], s[100:101]
	v_rcp_f32_e32 v152, v152
	v_rcp_f32_e32 v153, v153
	v_rcp_f32_e32 v154, v154
	v_rcp_f32_e32 v155, v155
	v_rcp_f32_e32 v156, v156
	v_rcp_f32_e32 v157, v157
	v_rcp_f32_e32 v158, v158
	v_rcp_f32_e32 v159, v159
	v_cvt_pk_bf16_f32 v124, v152, v153
	v_cvt_pk_bf16_f32 v125, v154, v155
	v_cvt_pk_bf16_f32 v126, v156, v157
	v_cvt_pk_bf16_f32 v127, v158, v159
	s_nop 1
	v_permlane16_swap_b32_e32 v124, v126
	v_permlane16_swap_b32_e32 v125, v127
	global_store_dwordx4 v[150:151], v[124:127], off
	v_pk_mul_f32 v[152:153], v[116:117], s[98:99]
	v_pk_mul_f32 v[154:155], v[118:119], s[98:99]
	v_pk_mul_f32 v[156:157], v[112:113], s[98:99]
	v_pk_mul_f32 v[158:159], v[114:115], s[98:99]
	v_exp_f32_e32 v152, v152
	v_exp_f32_e32 v153, v153
	v_exp_f32_e32 v154, v154
	v_exp_f32_e32 v155, v155
	v_exp_f32_e32 v156, v156
	v_exp_f32_e32 v157, v157
	v_exp_f32_e32 v158, v158
	v_exp_f32_e32 v159, v159
	v_pk_add_f32 v[152:153], v[152:153], s[100:101]
	v_pk_add_f32 v[154:155], v[154:155], s[100:101]
	v_pk_add_f32 v[156:157], v[156:157], s[100:101]
	v_pk_add_f32 v[158:159], v[158:159], s[100:101]
	v_rcp_f32_e32 v152, v152
	v_rcp_f32_e32 v153, v153
	v_rcp_f32_e32 v154, v154
	v_rcp_f32_e32 v155, v155
	v_rcp_f32_e32 v156, v156
	v_rcp_f32_e32 v157, v157
	v_rcp_f32_e32 v158, v158
	v_rcp_f32_e32 v159, v159
	v_cvt_pk_bf16_f32 v116, v152, v153
	v_cvt_pk_bf16_f32 v117, v154, v155
; __device__ __forceinline__ void st_bf4(bf16_t* p, f32x4 v) { u32x2 w; w.x = pk2(v[0], v[1]); w.y = pk2(v[2], v[3]); *(u32x2*)p = w; }
; __device__ __forceinline__ float sigmoidf_(float x) { return __builtin_amdgcn_rcpf(1.f + __expf(-x)); }
;     __device__ __forceinline__ void put(const Unit& u, int row, int col, f32x4 v) const {
;     ...
;         if (act == 1) v = v * 0.08838834764831845f;
;         else if (act == 2) { v[0] *= sigmoidf_(v[0]); v[1] *= sigmoidf_(v[1]); v[2] *= sigmoidf_(v[2]); v[3] *= sigmoidf_(v[3]); }
;         else if (act == 3) { v[0] = sigmoidf_(v[0]); v[1] = sigmoidf_(v[1]); v[2] = sigmoidf_(v[2]); v[3] = sigmoidf_(v[3]); }
;         st_bf4(base + (size_t)row * ldc + (col - c0), v);
	v_cvt_pk_bf16_f32 v118, v156, v157
	v_cvt_pk_bf16_f32 v119, v158, v159
	s_nop 1
	v_permlane16_swap_b32_e32 v116, v118
	v_permlane16_swap_b32_e32 v117, v119
	global_store_dwordx4 v[150:151], v[116:119], off offset:256
	s_nop 0
	v_lshl_add_u64 v[150:151], v[150:151], 0, s[44:45]
	v_pk_mul_f32 v[152:153], v[108:109], s[98:99]
	v_pk_mul_f32 v[154:155], v[110:111], s[98:99]
	v_pk_mul_f32 v[156:157], v[104:105], s[98:99]
	v_pk_mul_f32 v[158:159], v[106:107], s[98:99]
	v_exp_f32_e32 v152, v152
	v_exp_f32_e32 v153, v153
	v_exp_f32_e32 v154, v154
	v_exp_f32_e32 v155, v155
	v_exp_f32_e32 v156, v156
	v_exp_f32_e32 v157, v157
	v_exp_f32_e32 v158, v158
	v_exp_f32_e32 v159, v159
	v_pk_add_f32 v[152:153], v[152:153], s[100:101]
	v_pk_add_f32 v[154:155], v[154:155], s[100:101]
	v_pk_add_f32 v[156:157], v[156:157], s[100:101]
	v_pk_add_f32 v[158:159], v[158:159], s[100:101]
	v_rcp_f32_e32 v152, v152
	v_rcp_f32_e32 v153, v153
	v_rcp_f32_e32 v154, v154
	v_rcp_f32_e32 v155, v155
	v_rcp_f32_e32 v156, v156
	v_rcp_f32_e32 v157, v157
	v_rcp_f32_e32 v158, v158
	v_rcp_f32_e32 v159, v159
	v_cvt_pk_bf16_f32 v108, v152, v153
	v_cvt_pk_bf16_f32 v109, v154, v155
	v_cvt_pk_bf16_f32 v110, v156, v157
	v_cvt_pk_bf16_f32 v111, v158, v159
	s_nop 1
	v_permlane16_swap_b32_e32 v108, v110
	v_permlane16_swap_b32_e32 v109, v111
	global_store_dwordx4 v[150:151], v[108:111], off
	v_pk_mul_f32 v[152:153], v[100:101], s[98:99]
	v_pk_mul_f32 v[154:155], v[102:103], s[98:99]
	v_pk_mul_f32 v[156:157], v[96:97], s[98:99]
	v_pk_mul_f32 v[158:159], v[98:99], s[98:99]
	v_exp_f32_e32 v152, v152
	v_exp_f32_e32 v153, v153
	v_exp_f32_e32 v154, v154
	v_exp_f32_e32 v155, v155
	v_exp_f32_e32 v156, v156
	v_exp_f32_e32 v157, v157
	v_exp_f32_e32 v158, v158
	v_exp_f32_e32 v159, v159
	v_pk_add_f32 v[152:153], v[152:153], s[100:101]
	v_pk_add_f32 v[154:155], v[154:155], s[100:101]
	v_pk_add_f32 v[156:157], v[156:157], s[100:101]
	v_pk_add_f32 v[158:159], v[158:159], s[100:101]
	v_rcp_f32_e32 v152, v152
	v_rcp_f32_e32 v153, v153
	v_rcp_f32_e32 v154, v154
	v_rcp_f32_e32 v155, v155
	v_rcp_f32_e32 v156, v156
	v_rcp_f32_e32 v157, v157
	v_rcp_f32_e32 v158, v158
	v_rcp_f32_e32 v159, v159
	v_cvt_pk_bf16_f32 v100, v152, v153
	v_cvt_pk_bf16_f32 v101, v154, v155
	v_cvt_pk_bf16_f32 v102, v156, v157
	v_cvt_pk_bf16_f32 v103, v158, v159
	s_nop 1
	v_permlane16_swap_b32_e32 v100, v102
	v_permlane16_swap_b32_e32 v101, v103
	global_store_dwordx4 v[150:151], v[100:103], off offset:256
	s_nop 0
	v_lshl_add_u64 v[150:151], v[150:151], 0, s[44:45]
	v_pk_mul_f32 v[152:153], v[92:93], s[98:99]
	v_pk_mul_f32 v[154:155], v[94:95], s[98:99]
	v_pk_mul_f32 v[156:157], v[88:89], s[98:99]
	v_pk_mul_f32 v[158:159], v[90:91], s[98:99]
	v_exp_f32_e32 v152, v152
	v_exp_f32_e32 v153, v153
	v_exp_f32_e32 v154, v154
	v_exp_f32_e32 v155, v155
	v_exp_f32_e32 v156, v156
	v_exp_f32_e32 v157, v157
	v_exp_f32_e32 v158, v158
	v_exp_f32_e32 v159, v159
	v_pk_add_f32 v[152:153], v[152:153], s[100:101]
	v_pk_add_f32 v[154:155], v[154:155], s[100:101]
	v_pk_add_f32 v[156:157], v[156:157], s[100:101]
	v_pk_add_f32 v[158:159], v[158:159], s[100:101]
	v_rcp_f32_e32 v152, v152
	v_rcp_f32_e32 v153, v153
	v_rcp_f32_e32 v154, v154
	v_rcp_f32_e32 v155, v155
	v_rcp_f32_e32 v156, v156
	v_rcp_f32_e32 v157, v157
	v_rcp_f32_e32 v158, v158
	v_rcp_f32_e32 v159, v159
	v_cvt_pk_bf16_f32 v92, v152, v153
	v_cvt_pk_bf16_f32 v93, v154, v155
	v_cvt_pk_bf16_f32 v94, v156, v157
	v_cvt_pk_bf16_f32 v95, v158, v159
	s_nop 1
	v_permlane16_swap_b32_e32 v92, v94
	v_permlane16_swap_b32_e32 v93, v95
	global_store_dwordx4 v[150:151], v[92:95], off
	v_pk_mul_f32 v[152:153], v[84:85], s[98:99]
	v_pk_mul_f32 v[154:155], v[86:87], s[98:99]
	v_pk_mul_f32 v[156:157], v[80:81], s[98:99]
	v_pk_mul_f32 v[158:159], v[82:83], s[98:99]
	v_exp_f32_e32 v152, v152
	v_exp_f32_e32 v153, v153
	v_exp_f32_e32 v154, v154
	v_exp_f32_e32 v155, v155
	v_exp_f32_e32 v156, v156
	v_exp_f32_e32 v157, v157
	v_exp_f32_e32 v158, v158
	v_exp_f32_e32 v159, v159
	v_pk_add_f32 v[152:153], v[152:153], s[100:101]
	v_pk_add_f32 v[154:155], v[154:155], s[100:101]
	v_pk_add_f32 v[156:157], v[156:157], s[100:101]
	v_pk_add_f32 v[158:159], v[158:159], s[100:101]
	v_rcp_f32_e32 v152, v152
	v_rcp_f32_e32 v153, v153
	v_rcp_f32_e32 v154, v154
	v_rcp_f32_e32 v155, v155
	v_rcp_f32_e32 v156, v156
	v_rcp_f32_e32 v157, v157
	v_rcp_f32_e32 v158, v158
	v_rcp_f32_e32 v159, v159
	v_cvt_pk_bf16_f32 v84, v152, v153
	v_cvt_pk_bf16_f32 v85, v154, v155
	v_cvt_pk_bf16_f32 v86, v156, v157
	v_cvt_pk_bf16_f32 v87, v158, v159
	s_nop 1
	v_permlane16_swap_b32_e32 v84, v86
	v_permlane16_swap_b32_e32 v85, v87
	global_store_dwordx4 v[150:151], v[84:87], off offset:256
	s_nop 0
	v_lshl_add_u64 v[150:151], v[150:151], 0, s[44:45]
	v_pk_mul_f32 v[152:153], v[76:77], s[98:99]
	v_pk_mul_f32 v[154:155], v[78:79], s[98:99]
	v_pk_mul_f32 v[156:157], v[72:73], s[98:99]
	v_pk_mul_f32 v[158:159], v[74:75], s[98:99]
	v_exp_f32_e32 v152, v152
	v_exp_f32_e32 v153, v153
	v_exp_f32_e32 v154, v154
	v_exp_f32_e32 v155, v155
	v_exp_f32_e32 v156, v156
	v_exp_f32_e32 v157, v157
	v_exp_f32_e32 v158, v158
	v_exp_f32_e32 v159, v159
	v_pk_add_f32 v[152:153], v[152:153], s[100:101]
	v_pk_add_f32 v[154:155], v[154:155], s[100:101]
	v_pk_add_f32 v[156:157], v[156:157], s[100:101]
	v_pk_add_f32 v[158:159], v[158:159], s[100:101]
	v_rcp_f32_e32 v152, v152
	v_rcp_f32_e32 v153, v153
	v_rcp_f32_e32 v154, v154
	v_rcp_f32_e32 v155, v155
	v_rcp_f32_e32 v156, v156
	v_rcp_f32_e32 v157, v157
	v_rcp_f32_e32 v158, v158
	v_rcp_f32_e32 v159, v159
	v_cvt_pk_bf16_f32 v76, v152, v153
	v_cvt_pk_bf16_f32 v77, v154, v155
	v_cvt_pk_bf16_f32 v78, v156, v157
	v_cvt_pk_bf16_f32 v79, v158, v159
	s_nop 1
; __device__ __forceinline__ void st_bf4(bf16_t* p, f32x4 v) { u32x2 w; w.x = pk2(v[0], v[1]); w.y = pk2(v[2], v[3]); *(u32x2*)p = w; }
; __device__ __forceinline__ float sigmoidf_(float x) { return __builtin_amdgcn_rcpf(1.f + __expf(-x)); }
;     __device__ __forceinline__ void put(const Unit& u, int row, int col, f32x4 v) const {
;     ...
;         if (act == 1) v = v * 0.08838834764831845f;
;         else if (act == 2) { v[0] *= sigmoidf_(v[0]); v[1] *= sigmoidf_(v[1]); v[2] *= sigmoidf_(v[2]); v[3] *= sigmoidf_(v[3]); }
;         else if (act == 3) { v[0] = sigmoidf_(v[0]); v[1] = sigmoidf_(v[1]); v[2] = sigmoidf_(v[2]); v[3] = sigmoidf_(v[3]); }
;         st_bf4(base + (size_t)row * ldc + (col - c0), v);
	v_permlane16_swap_b32_e32 v76, v78
	v_permlane16_swap_b32_e32 v77, v79
	global_store_dwordx4 v[150:151], v[76:79], off
	v_pk_mul_f32 v[152:153], v[68:69], s[98:99]
	v_pk_mul_f32 v[154:155], v[70:71], s[98:99]
	v_pk_mul_f32 v[156:157], v[64:65], s[98:99]
	v_pk_mul_f32 v[158:159], v[66:67], s[98:99]
	v_exp_f32_e32 v152, v152
	v_exp_f32_e32 v153, v153
	v_exp_f32_e32 v154, v154
	v_exp_f32_e32 v155, v155
	v_exp_f32_e32 v156, v156
	v_exp_f32_e32 v157, v157
	v_exp_f32_e32 v158, v158
	v_exp_f32_e32 v159, v159
	v_pk_add_f32 v[152:153], v[152:153], s[100:101]
	v_pk_add_f32 v[154:155], v[154:155], s[100:101]
	v_pk_add_f32 v[156:157], v[156:157], s[100:101]
	v_pk_add_f32 v[158:159], v[158:159], s[100:101]
	v_rcp_f32_e32 v152, v152
	v_rcp_f32_e32 v153, v153
	v_rcp_f32_e32 v154, v154
	v_rcp_f32_e32 v155, v155
	v_rcp_f32_e32 v156, v156
	v_rcp_f32_e32 v157, v157
	v_rcp_f32_e32 v158, v158
	v_rcp_f32_e32 v159, v159
	v_cvt_pk_bf16_f32 v68, v152, v153
	v_cvt_pk_bf16_f32 v69, v154, v155
	v_cvt_pk_bf16_f32 v70, v156, v157
	v_cvt_pk_bf16_f32 v71, v158, v159
	s_nop 1
	v_permlane16_swap_b32_e32 v68, v70
	v_permlane16_swap_b32_e32 v69, v71
	global_store_dwordx4 v[150:151], v[68:71], off offset:256
	s_nop 0
	v_lshl_add_u64 v[150:151], v[150:151], 0, s[44:45]
	v_lshl_add_u64 v[150:151], v[150:151], 0, s[46:47]
	v_pk_mul_f32 v[152:153], v[60:61], s[98:99]
	v_pk_mul_f32 v[154:155], v[62:63], s[98:99]
	v_pk_mul_f32 v[156:157], v[56:57], s[98:99]
	v_pk_mul_f32 v[158:159], v[58:59], s[98:99]
	v_exp_f32_e32 v152, v152
	v_exp_f32_e32 v153, v153
	v_exp_f32_e32 v154, v154
	v_exp_f32_e32 v155, v155
	v_exp_f32_e32 v156, v156
	v_exp_f32_e32 v157, v157
	v_exp_f32_e32 v158, v158
	v_exp_f32_e32 v159, v159
	v_pk_add_f32 v[152:153], v[152:153], s[100:101]
	v_pk_add_f32 v[154:155], v[154:155], s[100:101]
	v_pk_add_f32 v[156:157], v[156:157], s[100:101]
	v_pk_add_f32 v[158:159], v[158:159], s[100:101]
	v_rcp_f32_e32 v152, v152
	v_rcp_f32_e32 v153, v153
	v_rcp_f32_e32 v154, v154
	v_rcp_f32_e32 v155, v155
	v_rcp_f32_e32 v156, v156
	v_rcp_f32_e32 v157, v157
	v_rcp_f32_e32 v158, v158
	v_rcp_f32_e32 v159, v159
	v_cvt_pk_bf16_f32 v60, v152, v153
	v_cvt_pk_bf16_f32 v61, v154, v155
	v_cvt_pk_bf16_f32 v62, v156, v157
	v_cvt_pk_bf16_f32 v63, v158, v159
	s_nop 1
	v_permlane16_swap_b32_e32 v60, v62
	v_permlane16_swap_b32_e32 v61, v63
	global_store_dwordx4 v[150:151], v[60:63], off
	v_pk_mul_f32 v[152:153], v[52:53], s[98:99]
	v_pk_mul_f32 v[154:155], v[54:55], s[98:99]
	v_pk_mul_f32 v[156:157], v[48:49], s[98:99]
	v_pk_mul_f32 v[158:159], v[50:51], s[98:99]
	v_exp_f32_e32 v152, v152
	v_exp_f32_e32 v153, v153
	v_exp_f32_e32 v154, v154
	v_exp_f32_e32 v155, v155
	v_exp_f32_e32 v156, v156
	v_exp_f32_e32 v157, v157
	v_exp_f32_e32 v158, v158
	v_exp_f32_e32 v159, v159
	v_pk_add_f32 v[152:153], v[152:153], s[100:101]
	v_pk_add_f32 v[154:155], v[154:155], s[100:101]
	v_pk_add_f32 v[156:157], v[156:157], s[100:101]
	v_pk_add_f32 v[158:159], v[158:159], s[100:101]
	v_rcp_f32_e32 v152, v152
	v_rcp_f32_e32 v153, v153
	v_rcp_f32_e32 v154, v154
	v_rcp_f32_e32 v155, v155
	v_rcp_f32_e32 v156, v156
	v_rcp_f32_e32 v157, v157
	v_rcp_f32_e32 v158, v158
	v_rcp_f32_e32 v159, v159
	v_cvt_pk_bf16_f32 v52, v152, v153
	v_cvt_pk_bf16_f32 v53, v154, v155
	v_cvt_pk_bf16_f32 v54, v156, v157
	v_cvt_pk_bf16_f32 v55, v158, v159
	s_nop 1
	v_permlane16_swap_b32_e32 v52, v54
	v_permlane16_swap_b32_e32 v53, v55
	global_store_dwordx4 v[150:151], v[52:55], off offset:256
	s_nop 0
	v_lshl_add_u64 v[150:151], v[150:151], 0, s[44:45]
	v_pk_mul_f32 v[152:153], v[44:45], s[98:99]
	v_pk_mul_f32 v[154:155], v[46:47], s[98:99]
	v_pk_mul_f32 v[156:157], v[40:41], s[98:99]
	v_pk_mul_f32 v[158:159], v[42:43], s[98:99]
	v_exp_f32_e32 v152, v152
	v_exp_f32_e32 v153, v153
	v_exp_f32_e32 v154, v154
	v_exp_f32_e32 v155, v155
	v_exp_f32_e32 v156, v156
	v_exp_f32_e32 v157, v157
	v_exp_f32_e32 v158, v158
	v_exp_f32_e32 v159, v159
	v_pk_add_f32 v[152:153], v[152:153], s[100:101]
	v_pk_add_f32 v[154:155], v[154:155], s[100:101]
	v_pk_add_f32 v[156:157], v[156:157], s[100:101]
	v_pk_add_f32 v[158:159], v[158:159], s[100:101]
	v_rcp_f32_e32 v152, v152
	v_rcp_f32_e32 v153, v153
	v_rcp_f32_e32 v154, v154
	v_rcp_f32_e32 v155, v155
	v_rcp_f32_e32 v156, v156
	v_rcp_f32_e32 v157, v157
	v_rcp_f32_e32 v158, v158
	v_rcp_f32_e32 v159, v159
	v_cvt_pk_bf16_f32 v44, v152, v153
	v_cvt_pk_bf16_f32 v45, v154, v155
	v_cvt_pk_bf16_f32 v46, v156, v157
	v_cvt_pk_bf16_f32 v47, v158, v159
	s_nop 1
	v_permlane16_swap_b32_e32 v44, v46
	v_permlane16_swap_b32_e32 v45, v47
	global_store_dwordx4 v[150:151], v[44:47], off
	v_pk_mul_f32 v[152:153], v[36:37], s[98:99]
	v_pk_mul_f32 v[154:155], v[38:39], s[98:99]
	v_pk_mul_f32 v[156:157], v[32:33], s[98:99]
	v_pk_mul_f32 v[158:159], v[34:35], s[98:99]
	v_exp_f32_e32 v152, v152
	v_exp_f32_e32 v153, v153
	v_exp_f32_e32 v154, v154
	v_exp_f32_e32 v155, v155
	v_exp_f32_e32 v156, v156
	v_exp_f32_e32 v157, v157
	v_exp_f32_e32 v158, v158
	v_exp_f32_e32 v159, v159
	v_pk_add_f32 v[152:153], v[152:153], s[100:101]
; __device__ __forceinline__ void st_bf4(bf16_t* p, f32x4 v) { u32x2 w; w.x = pk2(v[0], v[1]); w.y = pk2(v[2], v[3]); *(u32x2*)p = w; }
; __device__ __forceinline__ float sigmoidf_(float x) { return __builtin_amdgcn_rcpf(1.f + __expf(-x)); }
;     __device__ __forceinline__ void put(const Unit& u, int row, int col, f32x4 v) const {
;     ...
;         if (act == 1) v = v * 0.08838834764831845f;
;         else if (act == 2) { v[0] *= sigmoidf_(v[0]); v[1] *= sigmoidf_(v[1]); v[2] *= sigmoidf_(v[2]); v[3] *= sigmoidf_(v[3]); }
;         else if (act == 3) { v[0] = sigmoidf_(v[0]); v[1] = sigmoidf_(v[1]); v[2] = sigmoidf_(v[2]); v[3] = sigmoidf_(v[3]); }
;         st_bf4(base + (size_t)row * ldc + (col - c0), v);
	v_pk_add_f32 v[154:155], v[154:155], s[100:101]
	v_pk_add_f32 v[156:157], v[156:157], s[100:101]
	v_pk_add_f32 v[158:159], v[158:159], s[100:101]
	v_rcp_f32_e32 v152, v152
	v_rcp_f32_e32 v153, v153
	v_rcp_f32_e32 v154, v154
	v_rcp_f32_e32 v155, v155
	v_rcp_f32_e32 v156, v156
	v_rcp_f32_e32 v157, v157
	v_rcp_f32_e32 v158, v158
	v_rcp_f32_e32 v159, v159
	v_cvt_pk_bf16_f32 v36, v152, v153
	v_cvt_pk_bf16_f32 v37, v154, v155
	v_cvt_pk_bf16_f32 v38, v156, v157
	v_cvt_pk_bf16_f32 v39, v158, v159
	s_nop 1
	v_permlane16_swap_b32_e32 v36, v38
	v_permlane16_swap_b32_e32 v37, v39
	global_store_dwordx4 v[150:151], v[36:39], off offset:256
	s_nop 0
	v_lshl_add_u64 v[150:151], v[150:151], 0, s[44:45]
	v_pk_mul_f32 v[152:153], v[28:29], s[98:99]
	v_pk_mul_f32 v[154:155], v[30:31], s[98:99]
	v_pk_mul_f32 v[156:157], v[24:25], s[98:99]
	v_pk_mul_f32 v[158:159], v[26:27], s[98:99]
	v_exp_f32_e32 v152, v152
	v_exp_f32_e32 v153, v153
	v_exp_f32_e32 v154, v154
	v_exp_f32_e32 v155, v155
	v_exp_f32_e32 v156, v156
	v_exp_f32_e32 v157, v157
	v_exp_f32_e32 v158, v158
	v_exp_f32_e32 v159, v159
	v_pk_add_f32 v[152:153], v[152:153], s[100:101]
	v_pk_add_f32 v[154:155], v[154:155], s[100:101]
	v_pk_add_f32 v[156:157], v[156:157], s[100:101]
	v_pk_add_f32 v[158:159], v[158:159], s[100:101]
	v_rcp_f32_e32 v152, v152
	v_rcp_f32_e32 v153, v153
	v_rcp_f32_e32 v154, v154
	v_rcp_f32_e32 v155, v155
	v_rcp_f32_e32 v156, v156
	v_rcp_f32_e32 v157, v157
	v_rcp_f32_e32 v158, v158
	v_rcp_f32_e32 v159, v159
	v_cvt_pk_bf16_f32 v28, v152, v153
	v_cvt_pk_bf16_f32 v29, v154, v155
	v_cvt_pk_bf16_f32 v30, v156, v157
	v_cvt_pk_bf16_f32 v31, v158, v159
	s_nop 1
	v_permlane16_swap_b32_e32 v28, v30
	v_permlane16_swap_b32_e32 v29, v31
	global_store_dwordx4 v[150:151], v[28:31], off
	v_pk_mul_f32 v[152:153], v[20:21], s[98:99]
	v_pk_mul_f32 v[154:155], v[22:23], s[98:99]
	v_pk_mul_f32 v[156:157], v[16:17], s[98:99]
	v_pk_mul_f32 v[158:159], v[18:19], s[98:99]
	v_exp_f32_e32 v152, v152
	v_exp_f32_e32 v153, v153
	v_exp_f32_e32 v154, v154
	v_exp_f32_e32 v155, v155
	v_exp_f32_e32 v156, v156
	v_exp_f32_e32 v157, v157
	v_exp_f32_e32 v158, v158
	v_exp_f32_e32 v159, v159
	v_pk_add_f32 v[152:153], v[152:153], s[100:101]
	v_pk_add_f32 v[154:155], v[154:155], s[100:101]
	v_pk_add_f32 v[156:157], v[156:157], s[100:101]
	v_pk_add_f32 v[158:159], v[158:159], s[100:101]
	v_rcp_f32_e32 v152, v152
	v_rcp_f32_e32 v153, v153
	v_rcp_f32_e32 v154, v154
	v_rcp_f32_e32 v155, v155
	v_rcp_f32_e32 v156, v156
	v_rcp_f32_e32 v157, v157
	v_rcp_f32_e32 v158, v158
	v_rcp_f32_e32 v159, v159
	v_cvt_pk_bf16_f32 v20, v152, v153
	v_cvt_pk_bf16_f32 v21, v154, v155
	v_cvt_pk_bf16_f32 v22, v156, v157
	v_cvt_pk_bf16_f32 v23, v158, v159
	s_nop 1
	v_permlane16_swap_b32_e32 v20, v22
	v_permlane16_swap_b32_e32 v21, v23
	global_store_dwordx4 v[150:151], v[20:23], off offset:256
	s_nop 0
	v_lshl_add_u64 v[150:151], v[150:151], 0, s[44:45]
	v_pk_mul_f32 v[152:153], v[12:13], s[98:99]
	v_pk_mul_f32 v[154:155], v[14:15], s[98:99]
	v_pk_mul_f32 v[156:157], v[8:9], s[98:99]
	v_pk_mul_f32 v[158:159], v[10:11], s[98:99]
	v_exp_f32_e32 v152, v152
	v_exp_f32_e32 v153, v153
	v_exp_f32_e32 v154, v154
	v_exp_f32_e32 v155, v155
	v_exp_f32_e32 v156, v156
	v_exp_f32_e32 v157, v157
	v_exp_f32_e32 v158, v158
	v_exp_f32_e32 v159, v159
	v_pk_add_f32 v[152:153], v[152:153], s[100:101]
	v_pk_add_f32 v[154:155], v[154:155], s[100:101]
	v_pk_add_f32 v[156:157], v[156:157], s[100:101]
	v_pk_add_f32 v[158:159], v[158:159], s[100:101]
	v_rcp_f32_e32 v152, v152
	v_rcp_f32_e32 v153, v153
	v_rcp_f32_e32 v154, v154
	v_rcp_f32_e32 v155, v155
	v_rcp_f32_e32 v156, v156
	v_rcp_f32_e32 v157, v157
	v_rcp_f32_e32 v158, v158
	v_rcp_f32_e32 v159, v159
	v_cvt_pk_bf16_f32 v12, v152, v153
	v_cvt_pk_bf16_f32 v13, v154, v155
	v_cvt_pk_bf16_f32 v14, v156, v157
	v_cvt_pk_bf16_f32 v15, v158, v159
	s_nop 1
	v_permlane16_swap_b32_e32 v12, v14
	v_permlane16_swap_b32_e32 v13, v15
	global_store_dwordx4 v[150:151], v[12:15], off
	v_pk_mul_f32 v[152:153], v[4:5], s[98:99]
	v_pk_mul_f32 v[154:155], v[6:7], s[98:99]
	v_pk_mul_f32 v[156:157], v[0:1], s[98:99]
	v_pk_mul_f32 v[158:159], v[2:3], s[98:99]
	v_exp_f32_e32 v152, v152
	v_exp_f32_e32 v153, v153
	v_exp_f32_e32 v154, v154
	v_exp_f32_e32 v155, v155
	v_exp_f32_e32 v156, v156
	v_exp_f32_e32 v157, v157
	v_exp_f32_e32 v158, v158
	v_exp_f32_e32 v159, v159
	v_pk_add_f32 v[152:153], v[152:153], s[100:101]
	v_pk_add_f32 v[154:155], v[154:155], s[100:101]
	v_pk_add_f32 v[156:157], v[156:157], s[100:101]
	v_pk_add_f32 v[158:159], v[158:159], s[100:101]
	v_rcp_f32_e32 v152, v152
	v_rcp_f32_e32 v153, v153
	v_rcp_f32_e32 v154, v154
	v_rcp_f32_e32 v155, v155
	v_rcp_f32_e32 v156, v156
	v_rcp_f32_e32 v157, v157
	v_rcp_f32_e32 v158, v158
	v_rcp_f32_e32 v159, v159
	v_cvt_pk_bf16_f32 v4, v152, v153
	v_cvt_pk_bf16_f32 v5, v154, v155
	v_cvt_pk_bf16_f32 v6, v156, v157
	v_cvt_pk_bf16_f32 v7, v158, v159
	s_nop 1
	v_permlane16_swap_b32_e32 v4, v6
	v_permlane16_swap_b32_e32 v5, v7
	global_store_dwordx4 v[150:151], v[4:7], off offset:256
	s_branch .Lp2e_done
